# P2 start: params.ws reload replaced by SGPR copies (on top of hand-written grid barriers + sel fast path)
# baseline (speedup 1.0000x reference)
.LBB0_285:
	s_or_b64 exec, exec, s[0:1]
	v_mov_b32_e32 v2, 0x3308000
	s_waitcnt lgkmcnt(0)
	s_barrier
	v_mov_b32_e32 v0, s44
	v_mov_b32_e32 v1, s45
	global_load_dwordx2 v[48:49], v2, s[44:45] offset:128
	s_add_u32 s6, s44, 0x3308068
	s_addc_u32 s7, s45, 0
	s_add_u32 s56, s44, 0x33080d0
	s_addc_u32 s57, s45, 0
	s_cmpk_lt_i32 s52, 0x1000
	s_cselect_b64 s[58:59], -1, 0
	s_cmpk_gt_i32 s52, 0xfff
	s_waitcnt vmcnt(1)
	v_readfirstlane_b32 s4, v0
	v_readfirstlane_b32 s5, v1
	s_cbranch_scc1 .LBB0_312
	v_mov_b32_e32 v51, 0
	global_load_dwordx2 v[0:1], v51, s[6:7]
	s_add_u32 s8, s4, 0x3400000
	s_addc_u32 s9, s5, 0
	s_add_u32 s14, s4, 0x9000000
	s_addc_u32 s15, s5, 0
	s_add_u32 s16, s4, 0xa800000
	s_addc_u32 s17, s5, 0
	s_add_u32 s29, s4, 0x1b800000
	v_lshlrev_b32_e32 v50, 4, v176
	v_mbcnt_hi_u32_b32 v5, -1, v228
	s_addc_u32 s30, s5, 0
	s_mov_b64 s[2:3], 0xd000000
	v_lshlrev_b32_e32 v4, 4, v173
	v_lshl_add_u64 v[2:3], s[4:5], 0, v[50:51]
	v_and_b32_e32 v6, 64, v5
	s_add_u32 s31, s4, 0x1c400000
	v_and_b32_e32 v70, 48, v4
	v_xor_b32_e32 v4, 4, v5
	v_lshl_add_u64 v[54:55], v[2:3], 0, s[2:3]
	v_add_u32_e32 v2, 64, v6
	s_addc_u32 s33, s5, 0
	s_lshl_b32 s2, s18, 6
	s_lshl_b32 s3, s85, 3
	v_cmp_lt_i32_e32 vcc, v4, v2
	s_add_i32 s3, s3, s2
	v_lshlrev_b32_e32 v50, 5, v176
	v_cndmask_b32_e32 v2, v5, v4, vcc
	v_or_b32_e32 v72, s3, v174
	v_lshlrev_b32_e32 v52, 3, v176
	v_cmp_gt_u32_e64 s[0:1], 4, v176
	v_lshlrev_b32_e32 v53, 8, v176
	s_movk_i32 s24, 0x1200
	s_movk_i32 s25, 0xff
	s_mov_b32 s26, 0xffff0000
	v_mov_b32_e32 v68, 0x358637bd
	s_mov_b32 s27, 0xf800000
	v_mov_b32_e32 v69, 0x260
	s_movk_i32 s28, 0x7fff
	v_lshlrev_b32_e32 v71, 2, v2
	s_lshl_b32 s34, s46, 12
	s_lshl_b32 s35, s46, 6
	v_lshlrev_b32_e32 v73, 6, v72
	s_mov_b32 s36, s52
	s_waitcnt vmcnt(0)
	v_lshl_add_u64 v[56:57], v[0:1], 0, v[50:51]
	s_branch .LBB0_288
